# v52 with the preparation on 144 workgroups (27 more workgroups stream from the start)
# speedup vs baseline: 1.0494x; 1.0494x over previous
; __device__ __forceinline__ void p2_rwkv_prep(const Params& P, float* lds) {
;     const int tid = threadIdx.x, lane = tid & 63, wave = tid >> 6;
;     const bf16_t* prw = (const bf16_t*)(P.ws + WS_PRW);
;     float* RSB = (float*)(P.ws + WS_RSB);
;     constexpr int CT = 8, NCHK = NTK / CT;
;     float* xbuf = lds;
;     float* yt = lds + 2 * CT * 128 + wave * (2 * CT * 64);
;     float* ot = lds + 2 * CT * 128 + 8 * (2 * CT * 64) + wave * 768;
;     prep_bf16x8 wbh[2][4][2], wbl[2][4][2];
;     float w0c = 0.f, a0c = 0.f, kkc = 0.f, kac = 0.f, rkc = 0.f, mur = 0.f, muk = 0.f, muv = 0.f, mux = 0.f;
;     if (tid < RW) {
;         const prep_bf16x8* LF = (const prep_bf16x8*)(P.ws + WS_LFRAG);
; #pragma unroll
;         for (int mt = 0; mt < 2; ++mt)
; #pragma unroll
;             for (int nt = 0; nt < 4; ++nt)
; #pragma unroll
;                 for (int s = 0; s < 2; ++s) { const int fi = (((mt * 6 + wave) * 4 + nt) * 2 + s) * 64 + lane; wbh[mt][nt][s] = LF[fi]; wbl[mt][nt][s] = LF[2 * 6 * 4 * 2 * 64 + fi]; }
;         w0c = P.w0[tid]; a0c = P.a0[tid]; kkc = P.k_k[tid]; kac = P.k_a[tid]; rkc = P.r_k[tid];
;         mur = P.mu_shift[tid]; muk = P.mu_shift[RW + tid]; muv = P.mu_shift[2 * RW + tid];
;     } else {
; #pragma unroll
;         for (int mt = 0; mt < 2; ++mt)
; #pragma unroll
;             for (int nt = 0; nt < 4; ++nt)
; #pragma unroll
;                 for (int s = 0; s < 2; ++s)
; #pragma unroll
;                     for (int j = 0; j < 8; ++j) { wbh[mt][nt][s][j] = 0; wbl[mt][nt][s][j] = 0; }
;         mux = P.mu_shift[1152 + (tid - RW)];
;     }
;     int ch = blockIdx.x;
;     if (tid >= RW && ch < NCHK) prep_produce(P, prw, ch, xbuf, tid - RW, mux);
; __global__ void __launch_bounds__(512, 2) mk_fwd(Params P) {
;     ...
;     if (IN(2)) {
;         if (blockIdx.x < NPREP) {
;             p2_rwkv_prep(P, ldsf);
.LBB0_699:
	s_cmp_lt_i32 s60, 3
	s_cselect_b64 s[2:3], -1, 0
	s_and_b64 s[0:1], s[2:3], s[0:1]
	s_andn2_b64 vcc, exec, s[0:1]
	s_cbranch_vccnz .LBB0_939
	s_cmpk_gt_u32 s56, 0x8f
	s_cbranch_scc1 .LBB0_905
	s_movk_i32 s0, 0x180
	v_cmp_gt_u32_e64 s[4:5], s0, v0
	s_movk_i32 s0, 0x17f
	v_cmp_lt_u32_e32 vcc, s0, v0
	s_and_saveexec_b64 s[0:1], vcc
	s_xor_b64 s[0:1], exec, s[0:1]
	s_cbranch_execz .LBB0_703
	v_readlane_b32 s8, v252, 16
	v_lshlrev_b32_e32 v1, 2, v0
	v_readlane_b32 s18, v252, 26
	v_readlane_b32 s19, v252, 27
	v_readlane_b32 s9, v252, 17
	v_readlane_b32 s10, v252, 18
	v_readlane_b32 s11, v252, 19
	v_readlane_b32 s12, v252, 20
	v_readlane_b32 s13, v252, 21
	global_load_dword v173, v1, s[18:19] offset:3072
	v_readlane_b32 s14, v252, 22
	v_readlane_b32 s15, v252, 23
	v_readlane_b32 s16, v252, 24
	v_readlane_b32 s17, v252, 25
	v_readlane_b32 s20, v252, 28
	v_readlane_b32 s21, v252, 29
	v_readlane_b32 s22, v252, 30
	v_readlane_b32 s23, v252, 31

; __device__ __forceinline__ float bf2f(bf16_t b) { return __uint_as_float(((unsigned)b) << 16); }
; __device__ __forceinline__ void p2_rwkv_prep(const Params& P, float* lds) {
;     ...
;     int ch = blockIdx.x;
;     if (tid >= RW && ch < NCHK) prep_produce(P, prw, ch, xbuf, tid - RW, mux);
;     for (int it = 0; ch < NCHK; ch += NPREP, ++it) {
;         const int tok0 = ch * CT;
;         float* bufc = xbuf + (it & 1) * (CT * 128); float* bufn = xbuf + ((it + 1) & 1) * (CT * 128);
;         float nr[4], nk[4], nv[4], qr = 0.f, qk = 0.f, qv = 0.f;
;         if (tid < RW) {
; #pragma unroll
;             for (int q = 0; q < 4; ++q) { const bf16_t* p = prw + (size_t)(tok0 + q) * RCOLS + tid; nr[q] = bf2f(p[0]); nk[q] = bf2f(p[RW]); nv[q] = bf2f(p[2 * RW]); }
;             if (tok0 < NTOK && (tok0 & (SEQ - 1))) { const bf16_t* p = prw + (size_t)(tok0 - 1) * RCOLS + tid; qr = bf2f(p[0]); qk = bf2f(p[RW]); qv = bf2f(p[2 * RW]); }
;         }
.LBB0_760:
	s_or_b64 exec, exec, s[2:3]
	v_lshl_add_u32 v130, v170, 12, 0
	v_lshlrev_b32_e32 v132, 1, v0
	v_mov_b32_e32 v133, 0
	v_lshlrev_b32_e32 v134, 9, v0
	v_lshlrev_b32_e32 v172, 2, v1
	v_lshlrev_b32_e32 v131, 10, v170
	v_lshl_add_u64 v[176:177], s[0:1], 0, v[132:133]
	v_and_b32_e32 v134, 0xe00, v134
	v_and_b32_e32 v132, 0x60, v132
	v_add_u32_e32 v199, v130, v172
	s_load_dwordx16 s[36:51], s[58:59], 0x0
	v_add3_u32 v198, 0, v134, v132
	v_and_b32_e32 v132, 8, v0
	v_sub_u32_e32 v200, v199, v131
	v_cmp_eq_u32_e64 s[8:9], 0, v132
	v_and_b32_e32 v132, 15, v0
	v_mad_u32_u24 v131, v1, 12, v200
	s_add_u32 s18, s78, 0xa2d4000
	v_lshl_add_u32 v134, v132, 2, v130
	v_lshlrev_b32_e32 v130, 6, v0
	v_mad_i32_i24 v203, v1, -12, v131
	s_addc_u32 s19, s79, 0
	v_cmp_gt_u32_e64 s[10:11], 32, v1
	v_cmp_eq_u32_e64 s[12:13], 0, v1
	v_and_b32_e32 v130, 0x400, v130
	v_mad_u32_u24 v1, v1, 12, v203
	v_lshlrev_b32_e32 v132, 2, v0
	v_lshl_add_u64 v[180:181], v[174:175], 1, s[0:1]
	s_lshl_b32 s0, s56, 3
	v_mov_b32_e32 v171, v133
	v_cmp_gt_u32_e64 s[14:15], 64, v174
	s_movk_i32 s22, 0x400
	v_add_u32_e32 v201, 0xa000, v131
	v_add_u32_e32 v202, 0xa400, v131
	v_add_u32_e32 v204, 0xa600, v1
	v_add_u32_e32 v205, 0xaa00, v1
	v_lshl_add_u32 v206, v174, 2, 0
	s_waitcnt lgkmcnt(0)
	v_lshl_add_u64 v[178:179], s[50:51], 0, v[132:133]
	s_add_i32 s23, s0, 0x487
	s_mov_b32 s24, 0x3fb8aa3b
	s_movk_i32 s25, 0x610
	s_mov_b32 s26, 0x3f200000
	s_mov_b32 s27, 0xc2ce8ed0
	s_mov_b32 s28, 0x42b17218
	v_mov_b32_e32 v207, 0x3ca908c9
	s_brev_b32 s29, -2
	v_mov_b32_e32 v208, 0xa00
	v_add_u32_e32 v209, v134, v130
	v_mov_b32_e32 v210, 0x1400
	v_mov_b32_e32 v211, 0x610
	v_mov_b32_e32 v212, 0x7f800000
	s_mov_b32 s30, s56
	s_branch .LBB0_764

; __device__ __forceinline__ float bf2f(bf16_t b) { return __uint_as_float(((unsigned)b) << 16); }
; __device__ __forceinline__ void p2_rwkv_prep(const Params& P, float* lds) {
;     ...
;     for (int it = 0; ch < NCHK; ch += NPREP, ++it) {
;         const int tok0 = ch * CT;
;         float* bufc = xbuf + (it & 1) * (CT * 128); float* bufn = xbuf + ((it + 1) & 1) * (CT * 128);
;         float nr[4], nk[4], nv[4], qr = 0.f, qk = 0.f, qv = 0.f;
;         if (tid < RW) {
; #pragma unroll
;             for (int q = 0; q < 4; ++q) { const bf16_t* p = prw + (size_t)(tok0 + q) * RCOLS + tid; nr[q] = bf2f(p[0]); nk[q] = bf2f(p[RW]); nv[q] = bf2f(p[2 * RW]); }
;             if (tok0 < NTOK && (tok0 & (SEQ - 1))) { const bf16_t* p = prw + (size_t)(tok0 - 1) * RCOLS + tid; qr = bf2f(p[0]); qk = bf2f(p[RW]); qv = bf2f(p[2 * RW]); }
;         }
.LBB0_763:
	s_or_b64 exec, exec, s[0:1]
	s_add_i32 s0, s30, 0x90
	s_addk_i32 s23, 0x480
	s_addk_i32 s22, 0x400
	s_cmpk_lt_i32 s30, 0x774
	s_mov_b32 s30, s0
	s_cbranch_scc0 .LBB0_901
.LBB0_764:
	s_cmpk_gt_i32 s30, 0x7ff
	s_cselect_b64 s[98:99], -1, 0
	v_mov_b32_e32 v255, 1.0
	s_add_i32 s31, s23, 0xfffffb79
	v_mov_b32_e32 v131, 0
	v_mov_b32_e32 v130, 0
	v_mov_b32_e32 v1, 0
	s_and_saveexec_b64 s[0:1], s[4:5]
	s_cbranch_execz .LBB0_768
	v_mad_u64_u32 v[130:131], s[2:3], s31, v208, v[176:177]
	s_add_i32 s2, s23, 0xfffffb7a
	s_nop 0
	v_mad_u64_u32 v[134:135], s[2:3], s2, v208, v[176:177]
	s_add_i32 s2, s23, 0xfffffb7b
	s_nop 0
	v_mad_u64_u32 v[146:147], s[2:3], s2, v208, v[176:177]
	global_load_ushort v141, v[130:131], off
	global_load_ushort v144, v[130:131], off offset:768
	global_load_ushort v139, v[134:135], off
	global_load_ushort v142, v[134:135], off offset:768
	s_nop 0
	global_load_ushort v135, v[134:135], off offset:1536
	s_nop 0
	global_load_ushort v134, v[146:147], off
	global_load_ushort v138, v[146:147], off offset:768
	global_load_ushort v143, v[130:131], off offset:1536
	s_add_i32 s2, s23, 0xfffffb7c
	v_mad_u64_u32 v[130:131], s[2:3], s2, v208, v[176:177]
	global_load_ushort v136, v[130:131], off
	global_load_ushort v140, v[130:131], off offset:768
	global_load_ushort v132, v[130:131], off offset:1536
	global_load_ushort v137, v[146:147], off offset:1536
	s_cmpk_gt_i32 s30, 0x7ff
	s_cselect_b64 s[2:3], -1, 0
	s_and_b32 s16, s30, 0x1ff
	s_cmp_eq_u32 s16, 0
	s_cselect_b64 s[16:17], -1, 0
	s_or_b64 s[2:3], s[2:3], s[16:17]
	v_mov_b32_e32 v1, 0
	s_and_b64 vcc, exec, s[2:3]
	v_mov_b32_e32 v130, 0
	v_mov_b32_e32 v131, 0
	s_cbranch_vccnz .LBB0_767
	s_add_i32 s2, s23, 0xfffffb78
	v_mad_i64_i32 v[130:131], s[2:3], s2, v208, v[176:177]
	global_load_ushort v1, v[130:131], off
	global_load_ushort v145, v[130:131], off offset:1536
	global_load_ushort v146, v[130:131], off offset:768
	s_waitcnt vmcnt(0)
	v_lshlrev_b32_e32 v131, 16, v1
	v_lshlrev_b32_e32 v130, 16, v145
	v_lshlrev_b32_e32 v1, 16, v146

; __device__ __forceinline__ float bf2f(bf16_t b) { return __uint_as_float(((unsigned)b) << 16); }
; __device__ __forceinline__ float sigmoidf_(float x) { return 1.f / (1.f + __expf(-x)); }
; __device__ __forceinline__ void p2_rwkv_prep(const Params& P, float* lds) {
;     ...
;             for (int tk = tg; tk < tg + 4; ++tk) {
;                 const int tok = tok0 + tk;
;                 if (tok >= NTOK) { const float* p = P.state_shift + (size_t)(tok - NTOK) * RCOLS + tid; qr = p[0]; qk = p[RW]; qv = p[2 * RW]; }
;                 const float cr = nr[tk & 3], ck = nk[tk & 3], cv = nv[tk & 3];
;                 if (tk + 4 < CT) { const bf16_t* p = prw + (size_t)(tok + 4) * RCOLS + tid; nr[tk & 3] = bf2f(p[0]); nk[tk & 3] = bf2f(p[RW]); nv[tk & 3] = bf2f(p[2 * RW]); }
;                 const float r = cr + (qr - cr) * mur, kraw = ck + (qk - ck) * muk, v = cv + (qv - cv) * muv;
;                 qr = cr; qk = ck; qv = cv;
;                 const float aw = w0c + yt[tk * 64 + cc], aa = a0c + yt[(CT + tk) * 64 + cc];
;                 const float w = __expf(-DECAY_SCALE * sigmoidf_(aw)), a = sigmoidf_(aa);
;                 const float kkv = kraw * kkc;
;                 const float n2 = wave_sum_fast(kkv * kkv);
;                 const float kk = kkv * rsqrtf(fmaxf(n2, 1e-12f));
;                 const float kmod = kraw * (1.f + (a - 1.f) * kac);
;                 const float bb = kk * a;
;                 const float br = wave_sum_fast(bb * r);
;                 ekk[tk - tg] = kk; ew[tk - tg] = w; ebb[tk - tg] = bb; ekm[tk - tg] = kmod; ewr[tk - tg] = w * r - kk * br; ev[tk - tg] = v;
;                 ebr[tk - tg] = br; ekr[tk - tg] = wave_sum_fast(kmod * r); erk[tk - tg] = wave_sum_fast(r * kmod * rkc);
.LBB0_785:
	s_or_b64 exec, exec, s[2:3]
	s_waitcnt lgkmcnt(0)
	s_cmpk_gt_i32 s30, 0x7ff
	s_cselect_b64 s[2:3], -1, 0
	s_cmpk_lt_i32 s30, 0x800
	s_cbranch_scc1 .LBB0_787
	s_add_i32 s16, s23, 0xffffbb79
	v_mad_u64_u32 v[134:135], s[16:17], s16, v210, v[178:179]
	global_load_dword v131, v[134:135], off
	global_load_dword v1, v[134:135], off offset:1536
	global_load_dword v130, v[134:135], off offset:3072
.LBB0_787:
	s_add_i32 s16, s23, 0xfffffb7d
	v_mad_u64_u32 v[136:137], s[20:21], s16, v208, v[176:177]
	ds_read2st64_b32 v[134:135], v199 offset0:32 offset1:40
	global_load_ushort v156, v[136:137], off
	global_load_ushort v158, v[136:137], off offset:768
	global_load_ushort v157, v[136:137], off offset:1536
	s_waitcnt vmcnt(5)
	v_sub_f32_e32 v131, v131, v188
	v_fma_f32 v152, v196, v131, v188
	s_waitcnt vmcnt(4)
	v_sub_f32_e32 v1, v1, v189
	s_waitcnt lgkmcnt(0)
	v_add_f32_e32 v132, v194, v135
	v_mul_f32_e32 v132, 0xbfb8aa3b, v132
	v_exp_f32_e32 v132, v132
	v_mov_b32_e32 v136, v189
	v_fmac_f32_e32 v136, v195, v1
	v_mov_b32_e32 v167, v213
	v_add_f32_e32 v131, 1.0, v132
	v_div_scale_f32 v132, s[20:21], v131, v131, 1.0
	v_rcp_f32_e32 v135, v132
	s_nop 0
	v_fma_f32 v1, -v132, v135, 1.0
	v_fmac_f32_e32 v135, v1, v135
	v_div_scale_f32 v1, vcc, 1.0, v131, 1.0
	v_mul_f32_e32 v137, v1, v135
	v_fma_f32 v138, -v132, v137, v1
	v_fmac_f32_e32 v137, v138, v135
	v_fma_f32 v1, -v132, v137, v1
	v_mul_f32_e32 v132, v193, v136
	v_mul_f32_e32 v138, v132, v132
	v_div_fmas_f32 v1, v1, v135, v137
	v_div_fixup_f32 v1, v1, v131, 1.0
	v_mov_b32_dpp v138, v138 quad_perm:[1,0,3,2] row_mask:0xf bank_mask:0xf bound_ctrl:1
	v_fmac_f32_e32 v138, v132, v132
	v_add_f32_e32 v131, -1.0, v1
	v_fma_f32 v131, v192, v131, 1.0
	v_add_f32_dpp v138, v138, v138 quad_perm:[2,3,0,1] row_mask:0xf bank_mask:0xf bound_ctrl:1
	v_mul_f32_e32 v154, v136, v131
	s_andn2_b64 vcc, exec, s[2:3]
	v_add_f32_dpp v138, v138, v138 row_ror:4 row_mask:0xf bank_mask:0xf bound_ctrl:1
	s_nop 1
	v_add_f32_dpp v138, v138, v138 row_ror:8 row_mask:0xf bank_mask:0xf bound_ctrl:1
	v_mov_b32_e32 v139, v138
	s_nop 1
	v_permlane16_swap_b32_e32 v138, v139
	v_add_f32_e32 v138, v138, v139
	v_mov_b32_e32 v139, v138
	s_nop 1
	v_permlane32_swap_b32_e32 v138, v139
	v_add_f32_e32 v138, v138, v139
	v_max_f32_e32 v138, 0x2b8cbccc, v138
	v_rsq_f32_e32 v138, v138
	s_nop 0
	v_mul_f32_e32 v132, v132, v138
	v_mul_f32_e32 v155, v1, v132
	v_mul_f32_e32 v1, v152, v155
	s_nop 1
	v_mov_b32_dpp v1, v1 quad_perm:[1,0,3,2] row_mask:0xf bank_mask:0xf bound_ctrl:1
	v_fmac_f32_e32 v1, v152, v155
	s_nop 1
	v_add_f32_dpp v1, v1, v1 quad_perm:[2,3,0,1] row_mask:0xf bank_mask:0xf bound_ctrl:1
	s_nop 1
	v_add_f32_dpp v1, v1, v1 row_ror:4 row_mask:0xf bank_mask:0xf bound_ctrl:1
	s_nop 1
	v_add_f32_dpp v1, v1, v1 row_ror:8 row_mask:0xf bank_mask:0xf bound_ctrl:1
	v_mov_b32_e32 v131, v1
	s_nop 1
	v_permlane16_swap_b32_e32 v1, v131
	v_add_f32_e32 v136, v1, v131
	v_mul_f32_e32 v1, v152, v154
	v_mov_b32_e32 v150, v136
	s_nop 1
	v_permlane32_swap_b32_e32 v136, v150
	v_mov_b32_dpp v131, v1 quad_perm:[1,0,3,2] row_mask:0xf bank_mask:0xf bound_ctrl:1
	v_fmac_f32_e32 v131, v152, v154
	s_nop 1
	v_add_f32_dpp v131, v131, v131 quad_perm:[2,3,0,1] row_mask:0xf bank_mask:0xf bound_ctrl:1
	s_nop 1
	v_add_f32_dpp v131, v131, v131 row_ror:4 row_mask:0xf bank_mask:0xf bound_ctrl:1
	s_nop 1
	v_add_f32_dpp v131, v131, v131 row_ror:8 row_mask:0xf bank_mask:0xf bound_ctrl:1
	v_mov_b32_e32 v135, v131
	s_nop 1
	v_permlane16_swap_b32_e32 v131, v135
	v_add_f32_e32 v137, v131, v135
	v_mul_f32_e32 v131, v197, v1
	v_mov_b32_e32 v151, v137
	s_nop 1
	v_permlane32_swap_b32_e32 v137, v151
	v_mov_b32_dpp v131, v131 quad_perm:[1,0,3,2] row_mask:0xf bank_mask:0xf bound_ctrl:1
	v_fmac_f32_e32 v131, v197, v1
	s_nop 1
	v_add_f32_dpp v1, v131, v131 quad_perm:[2,3,0,1] row_mask:0xf bank_mask:0xf bound_ctrl:1
	s_nop 1
	v_add_f32_dpp v1, v1, v1 row_ror:4 row_mask:0xf bank_mask:0xf bound_ctrl:1
	s_nop 1
	v_add_f32_dpp v1, v1, v1 row_ror:8 row_mask:0xf bank_mask:0xf bound_ctrl:1
	v_mov_b32_e32 v131, v1
	s_nop 1
	v_permlane16_swap_b32_e32 v1, v131
	v_add_f32_e32 v168, v1, v131
	v_mov_b32_e32 v169, v168
	s_nop 1
	v_permlane32_swap_b32_e32 v168, v169
	s_cbranch_vccnz .LBB0_789
	s_add_i32 s2, s23, 0xffffbb7a
	v_mad_u64_u32 v[138:139], s[2:3], s2, v210, v[178:179]
	global_load_dword v188, v[138:139], off
	global_load_dword v189, v[138:139], off offset:1536
	global_load_dword v167, v[138:139], off offset:3072
; __device__ __forceinline__ float bf2f(bf16_t b) { return __uint_as_float(((unsigned)b) << 16); }
; __device__ __forceinline__ float sigmoidf_(float x) { return 1.f / (1.f + __expf(-x)); }
; __device__ __forceinline__ void p2_rwkv_prep(const Params& P, float* lds) {
;     ...
;             for (int tk = tg; tk < tg + 4; ++tk) {
;                 const int tok = tok0 + tk;
;                 if (tok >= NTOK) { const float* p = P.state_shift + (size_t)(tok - NTOK) * RCOLS + tid; qr = p[0]; qk = p[RW]; qv = p[2 * RW]; }
;                 const float cr = nr[tk & 3], ck = nk[tk & 3], cv = nv[tk & 3];
;                 if (tk + 4 < CT) { const bf16_t* p = prw + (size_t)(tok + 4) * RCOLS + tid; nr[tk & 3] = bf2f(p[0]); nk[tk & 3] = bf2f(p[RW]); nv[tk & 3] = bf2f(p[2 * RW]); }
;                 const float r = cr + (qr - cr) * mur, kraw = ck + (qk - ck) * muk, v = cv + (qv - cv) * muv;
;                 qr = cr; qk = ck; qv = cv;
;                 const float aw = w0c + yt[tk * 64 + cc], aa = a0c + yt[(CT + tk) * 64 + cc];
;                 const float w = __expf(-DECAY_SCALE * sigmoidf_(aw)), a = sigmoidf_(aa);
;                 const float kkv = kraw * kkc;
;                 const float n2 = wave_sum_fast(kkv * kkv);
;                 const float kk = kkv * rsqrtf(fmaxf(n2, 1e-12f));
;                 const float kmod = kraw * (1.f + (a - 1.f) * kac);
;                 const float bb = kk * a;
;                 const float br = wave_sum_fast(bb * r);
;                 ekk[tk - tg] = kk; ew[tk - tg] = w; ebb[tk - tg] = bb; ekm[tk - tg] = kmod; ewr[tk - tg] = w * r - kk * br; ev[tk - tg] = v;
;                 ebr[tk - tg] = br; ekr[tk - tg] = wave_sum_fast(kmod * r); erk[tk - tg] = wave_sum_fast(r * kmod * rkc);
.LBB0_789:
	s_add_i32 s17, s23, 0xfffffb7e
	v_mad_u64_u32 v[140:141], s[2:3], s17, v208, v[176:177]
	ds_read2st64_b32 v[138:139], v199 offset0:33 offset1:41
	global_load_ushort v159, v[140:141], off
	global_load_ushort v161, v[140:141], off offset:768
	global_load_ushort v160, v[140:141], off offset:1536
	s_waitcnt vmcnt(5)
	v_sub_f32_e32 v131, v188, v186
	s_waitcnt vmcnt(4)
	v_sub_f32_e32 v140, v189, v187
	v_mov_b32_e32 v141, v187
	s_waitcnt lgkmcnt(0)
	v_add_f32_e32 v1, v194, v139
	v_mul_f32_e32 v1, 0xbfb8aa3b, v1
	v_exp_f32_e32 v1, v1
	v_fma_f32 v139, v196, v131, v186
	v_fmac_f32_e32 v141, v195, v140
	s_add_i32 s33, s23, 0xfffffb7b
	v_add_f32_e32 v1, 1.0, v1
	v_div_scale_f32 v131, s[2:3], v1, v1, 1.0
	v_rcp_f32_e32 v135, v131
	s_cmpk_lt_i32 s33, 0x4000
	v_mov_b32_e32 v218, v214
	v_fma_f32 v140, -v131, v135, 1.0
	v_fmac_f32_e32 v135, v140, v135
	v_div_scale_f32 v140, vcc, 1.0, v1, 1.0
	v_mul_f32_e32 v142, v140, v135
	v_fma_f32 v143, -v131, v142, v140
	v_fmac_f32_e32 v142, v143, v135
	v_fma_f32 v131, -v131, v142, v140
	v_mul_f32_e32 v140, v193, v141
	v_mul_f32_e32 v143, v140, v140
	v_div_fmas_f32 v131, v131, v135, v142
	v_div_fixup_f32 v1, v131, v1, 1.0
	v_mov_b32_dpp v143, v143 quad_perm:[1,0,3,2] row_mask:0xf bank_mask:0xf bound_ctrl:1
	v_fmac_f32_e32 v143, v140, v140
	v_add_f32_e32 v131, -1.0, v1
	v_fma_f32 v131, v192, v131, 1.0
	v_add_f32_dpp v143, v143, v143 quad_perm:[2,3,0,1] row_mask:0xf bank_mask:0xf bound_ctrl:1
	v_mul_f32_e32 v189, v141, v131
	s_nop 0
	v_add_f32_dpp v143, v143, v143 row_ror:4 row_mask:0xf bank_mask:0xf bound_ctrl:1
	s_nop 1
	v_add_f32_dpp v143, v143, v143 row_ror:8 row_mask:0xf bank_mask:0xf bound_ctrl:1
	v_mov_b32_e32 v144, v143
	s_nop 1
	v_permlane16_swap_b32_e32 v143, v144
	v_add_f32_e32 v143, v143, v144
	v_mov_b32_e32 v144, v143
	s_nop 1
	v_permlane32_swap_b32_e32 v143, v144
	v_add_f32_e32 v143, v143, v144
	v_max_f32_e32 v143, 0x2b8cbccc, v143
	v_rsq_f32_e32 v143, v143
	s_nop 0
	v_mul_f32_e32 v188, v140, v143
	v_mul_f32_e32 v217, v1, v188
	v_mul_f32_e32 v1, v139, v217
	s_nop 1
	v_mov_b32_dpp v1, v1 quad_perm:[1,0,3,2] row_mask:0xf bank_mask:0xf bound_ctrl:1
	v_fmac_f32_e32 v1, v139, v217
	s_nop 1
	v_add_f32_dpp v1, v1, v1 quad_perm:[2,3,0,1] row_mask:0xf bank_mask:0xf bound_ctrl:1
	s_nop 1
	v_add_f32_dpp v1, v1, v1 row_ror:4 row_mask:0xf bank_mask:0xf bound_ctrl:1
	s_nop 1
	v_add_f32_dpp v1, v1, v1 row_ror:8 row_mask:0xf bank_mask:0xf bound_ctrl:1
	v_mov_b32_e32 v131, v1
	s_nop 1
	v_permlane16_swap_b32_e32 v1, v131
	v_add_f32_e32 v142, v1, v131
	v_mul_f32_e32 v1, v139, v189
	v_mov_b32_e32 v144, v142
	s_nop 1
	v_permlane32_swap_b32_e32 v142, v144
	v_mov_b32_dpp v131, v1 quad_perm:[1,0,3,2] row_mask:0xf bank_mask:0xf bound_ctrl:1
	v_fmac_f32_e32 v131, v139, v189
	s_nop 1
	v_add_f32_dpp v131, v131, v131 quad_perm:[2,3,0,1] row_mask:0xf bank_mask:0xf bound_ctrl:1
	s_nop 1
	v_add_f32_dpp v131, v131, v131 row_ror:4 row_mask:0xf bank_mask:0xf bound_ctrl:1
	s_nop 1
	v_add_f32_dpp v131, v131, v131 row_ror:8 row_mask:0xf bank_mask:0xf bound_ctrl:1
	v_mov_b32_e32 v135, v131
	s_nop 1
	v_permlane16_swap_b32_e32 v131, v135
	v_add_f32_e32 v143, v131, v135
	v_mul_f32_e32 v131, v197, v1
	v_mov_b32_e32 v145, v143
	s_nop 1
	v_permlane32_swap_b32_e32 v143, v145
	v_mov_b32_dpp v131, v131 quad_perm:[1,0,3,2] row_mask:0xf bank_mask:0xf bound_ctrl:1
	v_fmac_f32_e32 v131, v197, v1
	s_nop 1
	v_add_f32_dpp v1, v131, v131 quad_perm:[2,3,0,1] row_mask:0xf bank_mask:0xf bound_ctrl:1
	s_nop 1
	v_add_f32_dpp v1, v1, v1 row_ror:4 row_mask:0xf bank_mask:0xf bound_ctrl:1
	s_nop 1
	v_add_f32_dpp v1, v1, v1 row_ror:8 row_mask:0xf bank_mask:0xf bound_ctrl:1
	v_mov_b32_e32 v131, v1
	s_nop 1
	v_permlane16_swap_b32_e32 v1, v131
	v_add_f32_e32 v219, v1, v131
	v_mov_b32_e32 v220, v219
	s_nop 1
	v_permlane32_swap_b32_e32 v219, v220
	s_cbranch_scc1 .LBB0_791
	s_add_i32 s2, s23, 0xffffbb7b
	v_mad_u64_u32 v[140:141], s[2:3], s2, v210, v[178:179]
	global_load_dword v186, v[140:141], off
	global_load_dword v187, v[140:141], off offset:1536
	global_load_dword v218, v[140:141], off offset:3072
.LBB0_791:
	s_add_i32 s20, s23, 0xfffffb7f
	v_mad_u64_u32 v[146:147], s[2:3], s20, v208, v[176:177]
	ds_read2st64_b32 v[140:141], v199 offset0:34 offset1:42
	global_load_ushort v162, v[146:147], off
	global_load_ushort v164, v[146:147], off offset:768
	global_load_ushort v163, v[146:147], off offset:1536
	s_waitcnt vmcnt(5)
	v_sub_f32_e32 v131, v186, v184
	s_waitcnt vmcnt(4)
	v_sub_f32_e32 v146, v187, v185
	v_mov_b32_e32 v147, v185
	s_waitcnt lgkmcnt(0)
; __device__ __forceinline__ float bf2f(bf16_t b) { return __uint_as_float(((unsigned)b) << 16); }
; __device__ __forceinline__ float sigmoidf_(float x) { return 1.f / (1.f + __expf(-x)); }
; __device__ __forceinline__ void p2_rwkv_prep(const Params& P, float* lds) {
;     ...
;             for (int tk = tg; tk < tg + 4; ++tk) {
;                 const int tok = tok0 + tk;
;                 if (tok >= NTOK) { const float* p = P.state_shift + (size_t)(tok - NTOK) * RCOLS + tid; qr = p[0]; qk = p[RW]; qv = p[2 * RW]; }
;                 const float cr = nr[tk & 3], ck = nk[tk & 3], cv = nv[tk & 3];
;                 if (tk + 4 < CT) { const bf16_t* p = prw + (size_t)(tok + 4) * RCOLS + tid; nr[tk & 3] = bf2f(p[0]); nk[tk & 3] = bf2f(p[RW]); nv[tk & 3] = bf2f(p[2 * RW]); }
;                 const float r = cr + (qr - cr) * mur, kraw = ck + (qk - ck) * muk, v = cv + (qv - cv) * muv;
;                 qr = cr; qk = ck; qv = cv;
;                 const float aw = w0c + yt[tk * 64 + cc], aa = a0c + yt[(CT + tk) * 64 + cc];
;                 const float w = __expf(-DECAY_SCALE * sigmoidf_(aw)), a = sigmoidf_(aa);
;                 const float kkv = kraw * kkc;
;                 const float n2 = wave_sum_fast(kkv * kkv);
;                 const float kk = kkv * rsqrtf(fmaxf(n2, 1e-12f));
;                 const float kmod = kraw * (1.f + (a - 1.f) * kac);
;                 const float bb = kk * a;
;                 const float br = wave_sum_fast(bb * r);
;                 ekk[tk - tg] = kk; ew[tk - tg] = w; ebb[tk - tg] = bb; ekm[tk - tg] = kmod; ewr[tk - tg] = w * r - kk * br; ev[tk - tg] = v;
;                 ebr[tk - tg] = br; ekr[tk - tg] = wave_sum_fast(kmod * r); erk[tk - tg] = wave_sum_fast(r * kmod * rkc);
	v_add_f32_e32 v1, v194, v141
	v_mul_f32_e32 v1, 0xbfb8aa3b, v1
	v_exp_f32_e32 v1, v1
	v_fma_f32 v141, v196, v131, v184
	v_fmac_f32_e32 v147, v195, v146
	s_add_i32 s34, s23, 0xfffffb7c
	v_add_f32_e32 v1, 1.0, v1
	v_div_scale_f32 v131, s[2:3], v1, v1, 1.0
	v_rcp_f32_e32 v135, v131
	s_cmpk_lt_i32 s34, 0x4000
	v_mov_b32_e32 v222, v216
	v_fma_f32 v146, -v131, v135, 1.0
	v_fmac_f32_e32 v135, v146, v135
	v_div_scale_f32 v146, vcc, 1.0, v1, 1.0
	v_mul_f32_e32 v148, v146, v135
	v_fma_f32 v149, -v131, v148, v146
	v_fmac_f32_e32 v148, v149, v135
	v_fma_f32 v131, -v131, v148, v146
	v_mul_f32_e32 v146, v193, v147
	v_mul_f32_e32 v149, v146, v146
	v_div_fmas_f32 v131, v131, v135, v148
	v_div_fixup_f32 v1, v131, v1, 1.0
	v_mov_b32_dpp v149, v149 quad_perm:[1,0,3,2] row_mask:0xf bank_mask:0xf bound_ctrl:1
	v_fmac_f32_e32 v149, v146, v146
	v_add_f32_e32 v131, -1.0, v1
	v_fma_f32 v131, v192, v131, 1.0
	v_add_f32_dpp v149, v149, v149 quad_perm:[2,3,0,1] row_mask:0xf bank_mask:0xf bound_ctrl:1
	v_mul_f32_e32 v187, v147, v131
	s_nop 0
	v_add_f32_dpp v149, v149, v149 row_ror:4 row_mask:0xf bank_mask:0xf bound_ctrl:1
	s_nop 1
	v_add_f32_dpp v149, v149, v149 row_ror:8 row_mask:0xf bank_mask:0xf bound_ctrl:1
	v_mov_b32_e32 v153, v149
	s_nop 1
	v_permlane16_swap_b32_e32 v149, v153
	v_add_f32_e32 v149, v149, v153
	v_mov_b32_e32 v153, v149
	s_nop 1
	v_permlane32_swap_b32_e32 v149, v153
	v_add_f32_e32 v149, v149, v153
	v_max_f32_e32 v149, 0x2b8cbccc, v149
	v_rsq_f32_e32 v149, v149
	s_nop 0
	v_mul_f32_e32 v186, v146, v149
	v_mul_f32_e32 v221, v1, v186
	v_mul_f32_e32 v1, v141, v221
	s_nop 1
	v_mov_b32_dpp v1, v1 quad_perm:[1,0,3,2] row_mask:0xf bank_mask:0xf bound_ctrl:1
	v_fmac_f32_e32 v1, v141, v221
	s_nop 1
	v_add_f32_dpp v1, v1, v1 quad_perm:[2,3,0,1] row_mask:0xf bank_mask:0xf bound_ctrl:1
	s_nop 1
	v_add_f32_dpp v1, v1, v1 row_ror:4 row_mask:0xf bank_mask:0xf bound_ctrl:1
	s_nop 1
	v_add_f32_dpp v1, v1, v1 row_ror:8 row_mask:0xf bank_mask:0xf bound_ctrl:1
	v_mov_b32_e32 v131, v1
	s_nop 1
	v_permlane16_swap_b32_e32 v1, v131
	v_add_f32_e32 v146, v1, v131
	v_mul_f32_e32 v1, v141, v187
	v_mov_b32_e32 v148, v146
	s_nop 1
	v_permlane32_swap_b32_e32 v146, v148
	v_mov_b32_dpp v131, v1 quad_perm:[1,0,3,2] row_mask:0xf bank_mask:0xf bound_ctrl:1
	v_fmac_f32_e32 v131, v141, v187
	s_nop 1
	v_add_f32_dpp v131, v131, v131 quad_perm:[2,3,0,1] row_mask:0xf bank_mask:0xf bound_ctrl:1
	s_nop 1
	v_add_f32_dpp v131, v131, v131 row_ror:4 row_mask:0xf bank_mask:0xf bound_ctrl:1
	s_nop 1
	v_add_f32_dpp v131, v131, v131 row_ror:8 row_mask:0xf bank_mask:0xf bound_ctrl:1
	v_mov_b32_e32 v135, v131
	s_nop 1
	v_permlane16_swap_b32_e32 v131, v135
	v_add_f32_e32 v147, v131, v135
	v_mul_f32_e32 v131, v197, v1
	v_mov_b32_e32 v149, v147
	s_nop 1
	v_permlane32_swap_b32_e32 v147, v149
	v_mov_b32_dpp v131, v131 quad_perm:[1,0,3,2] row_mask:0xf bank_mask:0xf bound_ctrl:1
	v_fmac_f32_e32 v131, v197, v1
	s_nop 1
	v_add_f32_dpp v1, v131, v131 quad_perm:[2,3,0,1] row_mask:0xf bank_mask:0xf bound_ctrl:1
	s_nop 1
	v_add_f32_dpp v1, v1, v1 row_ror:4 row_mask:0xf bank_mask:0xf bound_ctrl:1
	s_nop 1
	v_add_f32_dpp v1, v1, v1 row_ror:8 row_mask:0xf bank_mask:0xf bound_ctrl:1
	v_mov_b32_e32 v131, v1
	s_nop 1
	v_permlane16_swap_b32_e32 v1, v131
	v_add_f32_e32 v223, v1, v131
	v_mov_b32_e32 v224, v223
	s_nop 1
	v_permlane32_swap_b32_e32 v223, v224
	s_cbranch_scc1 .LBB0_793
	s_add_i32 s2, s23, 0xffffbb7c
	v_mad_u64_u32 v[226:227], s[2:3], s2, v210, v[178:179]
	global_load_dword v184, v[226:227], off
	global_load_dword v185, v[226:227], off offset:1536
	global_load_dword v222, v[226:227], off offset:3072
; __device__ __forceinline__ float bf2f(bf16_t b) { return __uint_as_float(((unsigned)b) << 16); }
; __device__ __forceinline__ void p2_rwkv_prep(const Params& P, float* lds) {
;     ...
;             for (int tk = tg; tk < tg + 4; ++tk) {
;                 const int tok = tok0 + tk;
;                 if (tok >= NTOK) { const float* p = P.state_shift + (size_t)(tok - NTOK) * RCOLS + tid; qr = p[0]; qk = p[RW]; qv = p[2 * RW]; }
;                 const float cr = nr[tk & 3], ck = nk[tk & 3], cv = nv[tk & 3];
;                 if (tk + 4 < CT) { const bf16_t* p = prw + (size_t)(tok + 4) * RCOLS + tid; nr[tk & 3] = bf2f(p[0]); nk[tk & 3] = bf2f(p[RW]); nv[tk & 3] = bf2f(p[2 * RW]); }
;                 const float r = cr + (qr - cr) * mur, kraw = ck + (qk - ck) * muk, v = cv + (qv - cv) * muv;
;                 qr = cr; qk = ck; qv = cv;
;                 const float aw = w0c + yt[tk * 64 + cc], aa = a0c + yt[(CT + tk) * 64 + cc];
;                 const float w = __expf(-DECAY_SCALE * sigmoidf_(aw)), a = sigmoidf_(aa);
;                 const float kkv = kraw * kkc;
;                 const float n2 = wave_sum_fast(kkv * kkv);
;                 const float kk = kkv * rsqrtf(fmaxf(n2, 1e-12f));
;                 const float kmod = kraw * (1.f + (a - 1.f) * kac);
;                 const float bb = kk * a;
;                 const float br = wave_sum_fast(bb * r);
;                 ekk[tk - tg] = kk; ew[tk - tg] = w; ebb[tk - tg] = bb; ekm[tk - tg] = kmod; ewr[tk - tg] = w * r - kk * br; ev[tk - tg] = v;
;                 ebr[tk - tg] = br; ekr[tk - tg] = wave_sum_fast(kmod * r); erk[tk - tg] = wave_sum_fast(r * kmod * rkc);
;             }
; #pragma unroll
;             for (int tk = tg; tk < tg + 4; ++tk) {
;                 float* blk = RSB + ((size_t)(tok0 + tk) * RH + h) * RSB_BLK;
;                 float* oq = ot + (tk & 1) * 384;
;                 oq[cc] = ekk[tk - tg]; oq[64 + cc] = ew[tk - tg]; oq[128 + cc] = ebb[tk - tg]; oq[192 + cc] = ekm[tk - tg]; oq[256 + cc] = ewr[tk - tg]; oq[320 + cc] = ev[tk - tg];
;                 __builtin_amdgcn_wave_barrier();
;                 *(float4*)(blk + 4 * lane) = *(const float4*)(oq + 4 * lane);
;                 if (lane < 32) *(float4*)(blk + 256 + 4 * lane) = *(const float4*)(oq + 256 + 4 * lane);
;                 if (lane == 0) *(float4*)(blk + 384) = make_float4(ebr[tk - tg], ekr[tk - tg], erk[tk - tg], 0.f);
.LBB0_793:
	v_add_f32_e32 v1, v190, v134
	v_mul_f32_e32 v1, 0xbfb8aa3b, v1
	v_exp_f32_e32 v1, v1
	v_sub_f32_e32 v153, v130, v213
	v_pk_add_f32 v[134:135], v[136:137], v[150:151]
	s_add_i32 s21, s23, 0xfffffb80
	v_add_f32_e32 v1, 1.0, v1
	v_div_scale_f32 v130, s[2:3], v1, v1, 1.0
	v_rcp_f32_e32 v131, v130
	v_div_scale_f32 v136, vcc, 1.0, v1, 1.0
	s_waitcnt vmcnt(1)
	v_sub_f32_e32 v151, v185, v183
	v_fma_f32 v137, -v130, v131, 1.0
	v_fmac_f32_e32 v131, v137, v131
	v_mul_f32_e32 v137, v136, v131
	v_fma_f32 v150, -v130, v137, v136
	v_fmac_f32_e32 v137, v150, v131
	v_fma_f32 v130, -v130, v137, v136
	v_div_fmas_f32 v130, v130, v131, v137
	v_div_fixup_f32 v1, v130, v1, 1.0
	v_mul_f32_e32 v1, 0xbf1b4598, v1
	v_mul_f32_e32 v1, 0x3fb8aa3b, v1
	ds_read2st64_b32 v[130:131], v199 offset0:35 offset1:43
	v_exp_f32_e32 v228, v1
	v_mul_f32_e32 v1, v132, v134
	v_mad_u64_u32 v[136:137], s[2:3], s21, v208, v[176:177]
	v_fma_f32 v229, v152, v228, -v1
	s_waitcnt lgkmcnt(0)
	v_add_f32_e32 v1, v194, v131
	v_mul_f32_e32 v1, 0xbfb8aa3b, v1
	v_exp_f32_e32 v150, v1
	global_load_ushort v165, v[136:137], off
	global_load_ushort v166, v[136:137], off offset:768
	global_load_ushort v1, v[136:137], off offset:1536
	v_mov_b32_e32 v152, v183
	v_fmac_f32_e32 v152, v195, v151
	v_add_f32_e32 v136, 1.0, v150
	v_div_scale_f32 v137, s[2:3], v136, v136, 1.0
	v_rcp_f32_e32 v150, v137
	v_fmac_f32_e32 v213, v191, v153
	v_sub_f32_e32 v131, v184, v182
	v_fma_f32 v131, v196, v131, v182
	v_fma_f32 v151, -v137, v150, 1.0
	v_fmac_f32_e32 v150, v151, v150
	v_div_scale_f32 v151, vcc, 1.0, v136, 1.0
	v_mul_f32_e32 v153, v151, v150
	v_fma_f32 v184, -v137, v153, v151
	v_fmac_f32_e32 v153, v184, v150
	v_fma_f32 v137, -v137, v153, v151
	v_mul_f32_e32 v151, v193, v152
	v_mul_f32_e32 v184, v151, v151
	v_div_fmas_f32 v137, v137, v150, v153
	v_div_fixup_f32 v136, v137, v136, 1.0
	v_mov_b32_dpp v184, v184 quad_perm:[1,0,3,2] row_mask:0xf bank_mask:0xf bound_ctrl:1
	v_fmac_f32_e32 v184, v151, v151
	v_add_f32_e32 v137, -1.0, v136
	v_fma_f32 v137, v192, v137, 1.0
	v_add_f32_dpp v184, v184, v184 quad_perm:[2,3,0,1] row_mask:0xf bank_mask:0xf bound_ctrl:1
	s_mul_hi_u32 s35, s31, 6
	s_mul_i32 s31, s31, 6
	v_add_f32_dpp v184, v184, v184 row_ror:4 row_mask:0xf bank_mask:0xf bound_ctrl:1
	v_mul_f32_e32 v253, v132, v255
	v_mul_f32_e32 v254, v228, v255
	ds_write2st64_b32 v200, v253, v254 offset0:160 offset1:161
	v_mul_f32_e32 v253, v229, v255
	ds_write2st64_b32 v200, v253, v213 offset0:164 offset1:165
	v_cndmask_b32_e64 v255, v254, 1.0, s[98:99]
	v_rcp_f32_e32 v254, v255
	s_nop 0
	v_mul_f32_e32 v253, v155, v254
	v_mul_f32_e32 v254, v154, v254
	ds_write2st64_b32 v200, v253, v254 offset0:162 offset1:163
	v_add_f32_dpp v184, v184, v184 row_ror:8 row_mask:0xf bank_mask:0xf bound_ctrl:1
	v_mov_b32_e32 v185, v184
	s_nop 1
	v_permlane16_swap_b32_e32 v184, v185
	v_add_f32_e32 v184, v184, v185
	v_mov_b32_e32 v185, v184
	s_nop 1
	v_permlane32_swap_b32_e32 v184, v185
	v_add_f32_e32 v184, v184, v185
	v_max_f32_e32 v184, 0x2b8cbccc, v184
	v_rsq_f32_e32 v184, v184
	v_mul_f32_e32 v185, v152, v137
	ds_read_b128 v[228:231], v201
	v_or_b32_e32 v232, s31, v170
	v_mul_f32_e32 v184, v151, v184
	v_mul_f32_e32 v225, v136, v184
	v_mul_f32_e32 v136, v131, v225
	v_lshlrev_b32_e32 v132, 2, v172
	s_nop 0
	v_mov_b32_dpp v136, v136 quad_perm:[1,0,3,2] row_mask:0xf bank_mask:0xf bound_ctrl:1
	v_fmac_f32_e32 v136, v131, v225
	s_nop 1
	v_add_f32_dpp v136, v136, v136 quad_perm:[2,3,0,1] row_mask:0xf bank_mask:0xf bound_ctrl:1
	s_nop 1
	v_add_f32_dpp v136, v136, v136 row_ror:4 row_mask:0xf bank_mask:0xf bound_ctrl:1
	s_nop 1
	v_add_f32_dpp v136, v136, v136 row_ror:8 row_mask:0xf bank_mask:0xf bound_ctrl:1
	v_mov_b32_e32 v137, v136
	s_nop 1
	v_permlane16_swap_b32_e32 v136, v137
	v_add_f32_e32 v150, v136, v137
	v_mul_f32_e32 v136, v131, v185
	v_mov_b32_e32 v152, v150
	s_nop 1
	v_permlane32_swap_b32_e32 v150, v152
	v_mov_b32_dpp v137, v136 quad_perm:[1,0,3,2] row_mask:0xf bank_mask:0xf bound_ctrl:1
	v_fmac_f32_e32 v137, v131, v185
	s_nop 1
	v_add_f32_dpp v137, v137, v137 quad_perm:[2,3,0,1] row_mask:0xf bank_mask:0xf bound_ctrl:1
	s_nop 1
	v_add_f32_dpp v137, v137, v137 row_ror:4 row_mask:0xf bank_mask:0xf bound_ctrl:1
	s_nop 1
	v_add_f32_dpp v137, v137, v137 row_ror:8 row_mask:0xf bank_mask:0xf bound_ctrl:1
	v_mov_b32_e32 v151, v137
	s_nop 1
	v_permlane16_swap_b32_e32 v137, v151
	v_add_f32_e32 v151, v137, v151
	v_mul_f32_e32 v137, v197, v136
	v_mov_b32_e32 v153, v151
	s_nop 1
	v_permlane32_swap_b32_e32 v151, v153
	v_mov_b32_dpp v137, v137 quad_perm:[1,0,3,2] row_mask:0xf bank_mask:0xf bound_ctrl:1
	v_fmac_f32_e32 v137, v197, v136
	s_nop 1
	v_add_f32_dpp v136, v137, v137 quad_perm:[2,3,0,1] row_mask:0xf bank_mask:0xf bound_ctrl:1
	s_nop 1
	v_add_f32_dpp v136, v136, v136 row_ror:4 row_mask:0xf bank_mask:0xf bound_ctrl:1
	s_nop 1
	v_add_f32_dpp v136, v136, v136 row_ror:8 row_mask:0xf bank_mask:0xf bound_ctrl:1
	v_mov_b32_e32 v137, v136
	s_nop 1
	v_permlane16_swap_b32_e32 v136, v137
	v_add_f32_e32 v226, v136, v137
	v_mov_b64_e32 v[136:137], s[18:19]
	v_mad_u64_u32 v[154:155], s[2:3], v232, s25, v[136:137]
	v_mov_b32_e32 v227, v226
	v_mad_u32_u24 v155, s35, v211, v155
	s_nop 0
	v_permlane32_swap_b32_e32 v226, v227
	v_lshl_add_u64 v[136:137], v[154:155], 0, v[132:133]
	s_waitcnt lgkmcnt(0)
	global_store_dwordx4 v[136:137], v[228:231], off
	s_and_saveexec_b64 s[2:3], s[10:11]
	s_cbranch_execz .LBB0_795
	ds_read_b128 v[228:231], v202
	s_waitcnt lgkmcnt(0)
	global_store_dwordx4 v[136:137], v[228:231], off offset:1024

; __device__ __forceinline__ float sigmoidf_(float x) { return 1.f / (1.f + __expf(-x)); }
; __device__ __forceinline__ void p2_rwkv_prep(const Params& P, float* lds) {
;     ...
;                 const float aw = w0c + yt[tk * 64 + cc], aa = a0c + yt[(CT + tk) * 64 + cc];
;                 const float w = __expf(-DECAY_SCALE * sigmoidf_(aw)), a = sigmoidf_(aa);
;                 const float kkv = kraw * kkc;
;                 const float n2 = wave_sum_fast(kkv * kkv);
;                 const float kk = kkv * rsqrtf(fmaxf(n2, 1e-12f));
;                 const float kmod = kraw * (1.f + (a - 1.f) * kac);
;                 const float bb = kk * a;
;                 const float br = wave_sum_fast(bb * r);
;                 ekk[tk - tg] = kk; ew[tk - tg] = w; ebb[tk - tg] = bb; ekm[tk - tg] = kmod; ewr[tk - tg] = w * r - kk * br; ev[tk - tg] = v;
;                 ebr[tk - tg] = br; ekr[tk - tg] = wave_sum_fast(kmod * r); erk[tk - tg] = wave_sum_fast(r * kmod * rkc);
;             }
; #pragma unroll
;             for (int tk = tg; tk < tg + 4; ++tk) {
;                 float* blk = RSB + ((size_t)(tok0 + tk) * RH + h) * RSB_BLK;
;                 float* oq = ot + (tk & 1) * 384;
;                 oq[cc] = ekk[tk - tg]; oq[64 + cc] = ew[tk - tg]; oq[128 + cc] = ebb[tk - tg]; oq[192 + cc] = ekm[tk - tg]; oq[256 + cc] = ewr[tk - tg]; oq[320 + cc] = ev[tk - tg];
;                 __builtin_amdgcn_wave_barrier();
;                 *(float4*)(blk + 4 * lane) = *(const float4*)(oq + 4 * lane);
;                 if (lane < 32) *(float4*)(blk + 256 + 4 * lane) = *(const float4*)(oq + 256 + 4 * lane);
;                 if (lane == 0) *(float4*)(blk + 384) = make_float4(ebr[tk - tg], ekr[tk - tg], erk[tk - tg], 0.f);
.LBB0_797:
	s_or_b64 exec, exec, s[2:3]
	s_nop 0
	v_add_f32_e32 v134, v190, v138
	v_mul_f32_e32 v134, 0xbfb8aa3b, v134
	v_exp_f32_e32 v134, v134
	v_sub_f32_e32 v136, v167, v214
	v_fmac_f32_e32 v214, v191, v136
	v_add_f32_e32 v137, 1.0, v134
	v_div_scale_f32 v138, s[2:3], v137, v137, 1.0
	v_rcp_f32_e32 v154, v138
	v_pk_add_f32 v[134:135], v[142:143], v[144:145]
	v_div_scale_f32 v142, vcc, 1.0, v137, 1.0
	v_fma_f32 v143, -v138, v154, 1.0
	v_fmac_f32_e32 v154, v143, v154
	v_mul_f32_e32 v143, v142, v154
	v_fma_f32 v144, -v138, v143, v142
	v_fmac_f32_e32 v143, v144, v154
	v_fma_f32 v138, -v138, v143, v142
	v_div_fmas_f32 v138, v138, v154, v143
	v_div_fixup_f32 v137, v138, v137, 1.0
	v_mul_f32_e32 v137, 0xbf1b4598, v137
	v_mul_f32_e32 v137, 0x3fb8aa3b, v137
	v_exp_f32_e32 v142, v137
	v_mul_f32_e32 v136, v188, v134
	s_add_i32 s2, s23, 0xfffffb7a
	v_fma_f32 v143, v139, v142, -v136
	v_mul_f32_e32 v253, v188, v255
	v_mul_f32_e32 v254, v142, v255
	ds_write2st64_b32 v203, v253, v254 offset0:166 offset1:167
	v_mul_f32_e32 v253, v143, v255
	ds_write2st64_b32 v203, v253, v214 offset0:170 offset1:171
	v_cndmask_b32_e64 v255, v254, 1.0, s[98:99]
	v_rcp_f32_e32 v254, v255
	s_nop 0
	v_mul_f32_e32 v253, v217, v254
	v_mul_f32_e32 v254, v189, v254
	ds_write2st64_b32 v203, v253, v254 offset0:168 offset1:169
	ds_read_b128 v[142:145], v204
	v_mad_u64_u32 v[136:137], s[2:3], s2, 6, v[170:171]
	v_mov_b64_e32 v[138:139], s[18:19]
	v_mad_u64_u32 v[138:139], s[2:3], v136, s25, v[138:139]
	v_mad_u32_u24 v139, v137, s25, v139
	v_lshl_add_u64 v[136:137], v[138:139], 0, v[132:133]
	s_waitcnt lgkmcnt(0)
	global_store_dwordx4 v[136:137], v[142:145], off
	s_and_saveexec_b64 s[2:3], s[10:11]
	s_cbranch_execz .LBB0_799
	ds_read_b128 v[142:145], v205
	s_waitcnt lgkmcnt(0)
	global_store_dwordx4 v[136:137], v[142:145], off offset:1024

; __device__ __forceinline__ float bf2f(bf16_t b) { return __uint_as_float(((unsigned)b) << 16); }
; __device__ __forceinline__ float sigmoidf_(float x) { return 1.f / (1.f + __expf(-x)); }
; __device__ __forceinline__ void p2_rwkv_prep(const Params& P, float* lds) {
;     ...
;             for (int tk = tg; tk < tg + 4; ++tk) {
;                 const int tok = tok0 + tk;
;                 if (tok >= NTOK) { const float* p = P.state_shift + (size_t)(tok - NTOK) * RCOLS + tid; qr = p[0]; qk = p[RW]; qv = p[2 * RW]; }
;                 const float cr = nr[tk & 3], ck = nk[tk & 3], cv = nv[tk & 3];
;                 if (tk + 4 < CT) { const bf16_t* p = prw + (size_t)(tok + 4) * RCOLS + tid; nr[tk & 3] = bf2f(p[0]); nk[tk & 3] = bf2f(p[RW]); nv[tk & 3] = bf2f(p[2 * RW]); }
;                 const float r = cr + (qr - cr) * mur, kraw = ck + (qk - ck) * muk, v = cv + (qv - cv) * muv;
;                 qr = cr; qk = ck; qv = cv;
;                 const float aw = w0c + yt[tk * 64 + cc], aa = a0c + yt[(CT + tk) * 64 + cc];
;                 const float w = __expf(-DECAY_SCALE * sigmoidf_(aw)), a = sigmoidf_(aa);
;                 const float kkv = kraw * kkc;
;                 const float n2 = wave_sum_fast(kkv * kkv);
;                 const float kk = kkv * rsqrtf(fmaxf(n2, 1e-12f));
;                 const float kmod = kraw * (1.f + (a - 1.f) * kac);
;                 const float bb = kk * a;
;                 const float br = wave_sum_fast(bb * r);
;                 ekk[tk - tg] = kk; ew[tk - tg] = w; ebb[tk - tg] = bb; ekm[tk - tg] = kmod; ewr[tk - tg] = w * r - kk * br; ev[tk - tg] = v;
;                 ebr[tk - tg] = br; ekr[tk - tg] = wave_sum_fast(kmod * r); erk[tk - tg] = wave_sum_fast(r * kmod * rkc);
.LBB0_809:
	s_or_b64 exec, exec, s[2:3]
	s_cmpk_lt_i32 s16, 0x4000
	s_cbranch_scc1 .LBB0_811
	s_add_i32 s2, s23, 0xffffbb7d
	v_mad_u64_u32 v[130:131], s[2:3], s2, v210, v[178:179]
	global_load_dword v182, v[130:131], off
	global_load_dword v183, v[130:131], off offset:1536
	global_load_dword v215, v[130:131], off offset:3072
.LBB0_811:
	ds_read2st64_b32 v[134:135], v199 offset0:36 offset1:44
	v_lshlrev_b32_e32 v188, 16, v156
	s_waitcnt vmcnt(2)
	v_sub_f32_e32 v131, v182, v188
	v_fma_f32 v152, v196, v131, v188
	v_lshlrev_b32_e32 v189, 16, v158
	s_waitcnt lgkmcnt(0)
	v_add_f32_e32 v130, v194, v135
	v_mul_f32_e32 v130, 0xbfb8aa3b, v130
	v_exp_f32_e32 v130, v130
	s_waitcnt vmcnt(1)
	v_sub_f32_e32 v135, v183, v189
	v_fma_f32 v135, v195, v135, v189
	v_lshlrev_b32_e32 v213, 16, v157
	v_add_f32_e32 v130, 1.0, v130
	v_div_scale_f32 v131, s[2:3], v130, v130, 1.0
	v_rcp_f32_e32 v136, v131
	v_div_scale_f32 v137, vcc, 1.0, v130, 1.0
	s_cmpk_lt_i32 s17, 0x4000
	v_fma_f32 v138, -v131, v136, 1.0
	v_fmac_f32_e32 v136, v138, v136
	v_mul_f32_e32 v138, v137, v136
	v_fma_f32 v139, -v131, v138, v137
	v_fmac_f32_e32 v138, v139, v136
	v_fma_f32 v131, -v131, v138, v137
	v_mul_f32_e32 v137, v193, v135
	v_mul_f32_e32 v139, v137, v137
	v_div_fmas_f32 v131, v131, v136, v138
	v_div_fixup_f32 v130, v131, v130, 1.0
	v_mov_b32_dpp v139, v139 quad_perm:[1,0,3,2] row_mask:0xf bank_mask:0xf bound_ctrl:1
	v_fmac_f32_e32 v139, v137, v137
	v_add_f32_e32 v131, -1.0, v130
	v_fma_f32 v131, v192, v131, 1.0
	v_add_f32_dpp v139, v139, v139 quad_perm:[2,3,0,1] row_mask:0xf bank_mask:0xf bound_ctrl:1
	v_mul_f32_e32 v155, v135, v131
	v_mov_b32_e32 v157, v213
	v_add_f32_dpp v139, v139, v139 row_ror:4 row_mask:0xf bank_mask:0xf bound_ctrl:1
	v_mov_b32_e32 v138, v188
	s_nop 0
	v_add_f32_dpp v139, v139, v139 row_ror:8 row_mask:0xf bank_mask:0xf bound_ctrl:1
	v_mov_b32_e32 v140, v139
	s_nop 1
	v_permlane16_swap_b32_e32 v139, v140
	v_add_f32_e32 v139, v139, v140
	v_mov_b32_e32 v140, v139
	s_nop 1
	v_permlane32_swap_b32_e32 v139, v140
	v_add_f32_e32 v139, v139, v140
	v_max_f32_e32 v139, 0x2b8cbccc, v139
	v_rsq_f32_e32 v139, v139
	s_nop 0
	v_mul_f32_e32 v154, v137, v139
	v_mul_f32_e32 v156, v130, v154
	v_mul_f32_e32 v130, v152, v156
	s_nop 1
	v_mov_b32_dpp v130, v130 quad_perm:[1,0,3,2] row_mask:0xf bank_mask:0xf bound_ctrl:1
	v_fmac_f32_e32 v130, v152, v156
	s_nop 1
	v_add_f32_dpp v130, v130, v130 quad_perm:[2,3,0,1] row_mask:0xf bank_mask:0xf bound_ctrl:1
	s_nop 1
	v_add_f32_dpp v130, v130, v130 row_ror:4 row_mask:0xf bank_mask:0xf bound_ctrl:1
	s_nop 1
	v_add_f32_dpp v130, v130, v130 row_ror:8 row_mask:0xf bank_mask:0xf bound_ctrl:1
	v_mov_b32_e32 v131, v130
	s_nop 1
	v_permlane16_swap_b32_e32 v130, v131
	v_add_f32_e32 v136, v130, v131
	v_mul_f32_e32 v130, v152, v155
	v_mov_b32_e32 v148, v136
	s_nop 1
	v_permlane32_swap_b32_e32 v136, v148
	v_mov_b32_dpp v131, v130 quad_perm:[1,0,3,2] row_mask:0xf bank_mask:0xf bound_ctrl:1
	v_fmac_f32_e32 v131, v152, v155
	s_nop 1
	v_add_f32_dpp v131, v131, v131 quad_perm:[2,3,0,1] row_mask:0xf bank_mask:0xf bound_ctrl:1
	s_nop 1
	v_add_f32_dpp v131, v131, v131 row_ror:4 row_mask:0xf bank_mask:0xf bound_ctrl:1
	s_nop 1
	v_add_f32_dpp v131, v131, v131 row_ror:8 row_mask:0xf bank_mask:0xf bound_ctrl:1
	v_mov_b32_e32 v135, v131
	s_nop 1
	v_permlane16_swap_b32_e32 v131, v135
	v_add_f32_e32 v137, v131, v135
	v_mul_f32_e32 v131, v197, v130
	v_mov_b32_e32 v149, v137
	s_nop 1
	v_permlane32_swap_b32_e32 v137, v149
	v_mov_b32_dpp v131, v131 quad_perm:[1,0,3,2] row_mask:0xf bank_mask:0xf bound_ctrl:1
	v_fmac_f32_e32 v131, v197, v130
	v_mov_b32_e32 v135, v189
	s_nop 0
	v_add_f32_dpp v130, v131, v131 quad_perm:[2,3,0,1] row_mask:0xf bank_mask:0xf bound_ctrl:1
	s_nop 1
	v_add_f32_dpp v130, v130, v130 row_ror:4 row_mask:0xf bank_mask:0xf bound_ctrl:1
	s_nop 1
	v_add_f32_dpp v130, v130, v130 row_ror:8 row_mask:0xf bank_mask:0xf bound_ctrl:1
	v_mov_b32_e32 v131, v130
	s_nop 1
	v_permlane16_swap_b32_e32 v130, v131
	v_add_f32_e32 v158, v130, v131
	v_mov_b32_e32 v167, v158
	s_nop 1
	v_permlane32_swap_b32_e32 v158, v167
	s_cbranch_scc1 .LBB0_813
	s_add_i32 s2, s23, 0xffffbb7e
	v_mad_u64_u32 v[130:131], s[2:3], s2, v210, v[178:179]
	global_load_dword v138, v[130:131], off
	global_load_dword v135, v[130:131], off offset:1536
	global_load_dword v157, v[130:131], off offset:3072
; __device__ __forceinline__ float bf2f(bf16_t b) { return __uint_as_float(((unsigned)b) << 16); }
; __device__ __forceinline__ float sigmoidf_(float x) { return 1.f / (1.f + __expf(-x)); }
; __device__ __forceinline__ void p2_rwkv_prep(const Params& P, float* lds) {
;     ...
;             for (int tk = tg; tk < tg + 4; ++tk) {
;                 const int tok = tok0 + tk;
;                 if (tok >= NTOK) { const float* p = P.state_shift + (size_t)(tok - NTOK) * RCOLS + tid; qr = p[0]; qk = p[RW]; qv = p[2 * RW]; }
;                 const float cr = nr[tk & 3], ck = nk[tk & 3], cv = nv[tk & 3];
;                 if (tk + 4 < CT) { const bf16_t* p = prw + (size_t)(tok + 4) * RCOLS + tid; nr[tk & 3] = bf2f(p[0]); nk[tk & 3] = bf2f(p[RW]); nv[tk & 3] = bf2f(p[2 * RW]); }
;                 const float r = cr + (qr - cr) * mur, kraw = ck + (qk - ck) * muk, v = cv + (qv - cv) * muv;
;                 qr = cr; qk = ck; qv = cv;
;                 const float aw = w0c + yt[tk * 64 + cc], aa = a0c + yt[(CT + tk) * 64 + cc];
;                 const float w = __expf(-DECAY_SCALE * sigmoidf_(aw)), a = sigmoidf_(aa);
;                 const float kkv = kraw * kkc;
;                 const float n2 = wave_sum_fast(kkv * kkv);
;                 const float kk = kkv * rsqrtf(fmaxf(n2, 1e-12f));
;                 const float kmod = kraw * (1.f + (a - 1.f) * kac);
;                 const float bb = kk * a;
;                 const float br = wave_sum_fast(bb * r);
;                 ekk[tk - tg] = kk; ew[tk - tg] = w; ebb[tk - tg] = bb; ekm[tk - tg] = kmod; ewr[tk - tg] = w * r - kk * br; ev[tk - tg] = v;
;                 ebr[tk - tg] = br; ekr[tk - tg] = wave_sum_fast(kmod * r); erk[tk - tg] = wave_sum_fast(r * kmod * rkc);
.LBB0_813:
	ds_read2st64_b32 v[130:131], v199 offset0:37 offset1:45
	v_lshlrev_b32_e32 v186, 16, v159
	v_lshlrev_b32_e32 v187, 16, v161
	s_waitcnt vmcnt(1)
	v_sub_f32_e32 v135, v135, v187
	v_fma_f32 v135, v195, v135, v187
	s_waitcnt lgkmcnt(0)
	v_add_f32_e32 v131, v194, v131
	v_mul_f32_e32 v131, 0xbfb8aa3b, v131
	v_exp_f32_e32 v139, v131
	v_sub_f32_e32 v131, v138, v186
	v_fma_f32 v131, v196, v131, v186
	v_lshlrev_b32_e32 v214, 16, v160
	v_add_f32_e32 v138, 1.0, v139
	v_div_scale_f32 v139, s[2:3], v138, v138, 1.0
	v_rcp_f32_e32 v140, v139
	v_div_scale_f32 v141, vcc, 1.0, v138, 1.0
	s_cmpk_lt_i32 s20, 0x4000
	v_fma_f32 v142, -v139, v140, 1.0
	v_fmac_f32_e32 v140, v142, v140
	v_mul_f32_e32 v142, v141, v140
	v_fma_f32 v143, -v139, v142, v141
	v_fmac_f32_e32 v142, v143, v140
	v_fma_f32 v139, -v139, v142, v141
	v_mul_f32_e32 v141, v193, v135
	v_mul_f32_e32 v143, v141, v141
	v_div_fmas_f32 v139, v139, v140, v142
	v_div_fixup_f32 v138, v139, v138, 1.0
	v_mov_b32_dpp v143, v143 quad_perm:[1,0,3,2] row_mask:0xf bank_mask:0xf bound_ctrl:1
	v_fmac_f32_e32 v143, v141, v141
	v_add_f32_e32 v139, -1.0, v138
	v_fma_f32 v139, v192, v139, 1.0
	v_add_f32_dpp v143, v143, v143 quad_perm:[2,3,0,1] row_mask:0xf bank_mask:0xf bound_ctrl:1
	v_mul_f32_e32 v160, v135, v139
	v_mov_b32_e32 v168, v214
	v_add_f32_dpp v143, v143, v143 row_ror:4 row_mask:0xf bank_mask:0xf bound_ctrl:1
	s_nop 1
	v_add_f32_dpp v143, v143, v143 row_ror:8 row_mask:0xf bank_mask:0xf bound_ctrl:1
	v_mov_b32_e32 v144, v143
	s_nop 1
	v_permlane16_swap_b32_e32 v143, v144
	v_add_f32_e32 v143, v143, v144
	v_mov_b32_e32 v144, v143
	s_nop 1
	v_permlane32_swap_b32_e32 v143, v144
	v_add_f32_e32 v143, v143, v144
	v_max_f32_e32 v143, 0x2b8cbccc, v143
	v_rsq_f32_e32 v143, v143
	v_mov_b32_e32 v144, v186
	v_mul_f32_e32 v159, v141, v143
	v_mul_f32_e32 v161, v138, v159
	v_mul_f32_e32 v135, v131, v161
	s_nop 1
	v_mov_b32_dpp v135, v135 quad_perm:[1,0,3,2] row_mask:0xf bank_mask:0xf bound_ctrl:1
	v_fmac_f32_e32 v135, v131, v161
	s_nop 1
	v_add_f32_dpp v135, v135, v135 quad_perm:[2,3,0,1] row_mask:0xf bank_mask:0xf bound_ctrl:1
	s_nop 1
	v_add_f32_dpp v135, v135, v135 row_ror:4 row_mask:0xf bank_mask:0xf bound_ctrl:1
	s_nop 1
	v_add_f32_dpp v135, v135, v135 row_ror:8 row_mask:0xf bank_mask:0xf bound_ctrl:1
	v_mov_b32_e32 v138, v135
	s_nop 1
	v_permlane16_swap_b32_e32 v135, v138
	v_add_f32_e32 v138, v135, v138
	v_mul_f32_e32 v135, v131, v160
	v_mul_f32_e32 v142, v197, v135
	v_mov_b32_e32 v140, v138
	v_mov_b32_dpp v139, v135 quad_perm:[1,0,3,2] row_mask:0xf bank_mask:0xf bound_ctrl:1
	v_mov_b32_dpp v142, v142 quad_perm:[1,0,3,2] row_mask:0xf bank_mask:0xf bound_ctrl:1
	v_fmac_f32_e32 v139, v131, v160
	v_fmac_f32_e32 v142, v197, v135
	v_permlane32_swap_b32_e32 v138, v140
	v_add_f32_dpp v139, v139, v139 quad_perm:[2,3,0,1] row_mask:0xf bank_mask:0xf bound_ctrl:1
	v_add_f32_dpp v135, v142, v142 quad_perm:[2,3,0,1] row_mask:0xf bank_mask:0xf bound_ctrl:1
	s_nop 0
	v_add_f32_dpp v139, v139, v139 row_ror:4 row_mask:0xf bank_mask:0xf bound_ctrl:1
	v_add_f32_dpp v135, v135, v135 row_ror:4 row_mask:0xf bank_mask:0xf bound_ctrl:1
	s_nop 0
	v_add_f32_dpp v139, v139, v139 row_ror:8 row_mask:0xf bank_mask:0xf bound_ctrl:1
	v_add_f32_dpp v135, v135, v135 row_ror:8 row_mask:0xf bank_mask:0xf bound_ctrl:1
	v_mov_b32_e32 v141, v139
	v_mov_b32_e32 v142, v135
	s_nop 0
	v_permlane16_swap_b32_e32 v139, v141
	v_permlane16_swap_b32_e32 v135, v142
	v_add_f32_e32 v139, v139, v141
	v_add_f32_e32 v169, v135, v142
	v_mov_b32_e32 v141, v139
	v_mov_b32_e32 v217, v169
	s_nop 0
	v_permlane32_swap_b32_e32 v139, v141
	v_permlane32_swap_b32_e32 v169, v217
	v_mov_b32_e32 v135, v187
	s_cbranch_scc1 .LBB0_815
	s_add_i32 s2, s23, 0xffffbb7f
	v_mad_u64_u32 v[142:143], s[2:3], s2, v210, v[178:179]
	global_load_dword v144, v[142:143], off
	global_load_dword v135, v[142:143], off offset:1536
	global_load_dword v168, v[142:143], off offset:3072
; __device__ __forceinline__ float bf2f(bf16_t b) { return __uint_as_float(((unsigned)b) << 16); }
; __device__ __forceinline__ float sigmoidf_(float x) { return 1.f / (1.f + __expf(-x)); }
; __device__ __forceinline__ void p2_rwkv_prep(const Params& P, float* lds) {
;     ...
;             for (int tk = tg; tk < tg + 4; ++tk) {
;                 const int tok = tok0 + tk;
;                 if (tok >= NTOK) { const float* p = P.state_shift + (size_t)(tok - NTOK) * RCOLS + tid; qr = p[0]; qk = p[RW]; qv = p[2 * RW]; }
;                 const float cr = nr[tk & 3], ck = nk[tk & 3], cv = nv[tk & 3];
;                 if (tk + 4 < CT) { const bf16_t* p = prw + (size_t)(tok + 4) * RCOLS + tid; nr[tk & 3] = bf2f(p[0]); nk[tk & 3] = bf2f(p[RW]); nv[tk & 3] = bf2f(p[2 * RW]); }
;                 const float r = cr + (qr - cr) * mur, kraw = ck + (qk - ck) * muk, v = cv + (qv - cv) * muv;
;                 qr = cr; qk = ck; qv = cv;
;                 const float aw = w0c + yt[tk * 64 + cc], aa = a0c + yt[(CT + tk) * 64 + cc];
;                 const float w = __expf(-DECAY_SCALE * sigmoidf_(aw)), a = sigmoidf_(aa);
;                 const float kkv = kraw * kkc;
;                 const float n2 = wave_sum_fast(kkv * kkv);
;                 const float kk = kkv * rsqrtf(fmaxf(n2, 1e-12f));
;                 const float kmod = kraw * (1.f + (a - 1.f) * kac);
;                 const float bb = kk * a;
;                 const float br = wave_sum_fast(bb * r);
;                 ekk[tk - tg] = kk; ew[tk - tg] = w; ebb[tk - tg] = bb; ekm[tk - tg] = kmod; ewr[tk - tg] = w * r - kk * br; ev[tk - tg] = v;
;                 ebr[tk - tg] = br; ekr[tk - tg] = wave_sum_fast(kmod * r); erk[tk - tg] = wave_sum_fast(r * kmod * rkc);
.LBB0_815:
	ds_read2st64_b32 v[142:143], v199 offset0:38 offset1:46
	v_lshlrev_b32_e32 v184, 16, v162
	v_lshlrev_b32_e32 v185, 16, v164
	s_waitcnt vmcnt(1)
	v_sub_f32_e32 v135, v135, v185
	v_fma_f32 v135, v195, v135, v185
	s_waitcnt lgkmcnt(0)
	v_add_f32_e32 v143, v194, v143
	v_mul_f32_e32 v143, 0xbfb8aa3b, v143
	v_exp_f32_e32 v145, v143
	v_sub_f32_e32 v143, v144, v184
	v_lshlrev_b32_e32 v216, 16, v163
	v_fma_f32 v143, v196, v143, v184
	v_add_f32_e32 v144, 1.0, v145
	v_div_scale_f32 v145, s[2:3], v144, v144, 1.0
	v_rcp_f32_e32 v146, v145
	v_div_scale_f32 v147, vcc, 1.0, v144, 1.0
	s_cmpk_lt_i32 s21, 0x4000
	v_fma_f32 v150, -v145, v146, 1.0
	v_fmac_f32_e32 v146, v150, v146
	v_mul_f32_e32 v150, v147, v146
	v_fma_f32 v151, -v145, v150, v147
	v_fmac_f32_e32 v150, v151, v146
	v_fma_f32 v145, -v145, v150, v147
	v_mul_f32_e32 v147, v193, v135
	v_mul_f32_e32 v151, v147, v147
	v_div_fmas_f32 v145, v145, v146, v150
	v_div_fixup_f32 v144, v145, v144, 1.0
	v_mov_b32_dpp v151, v151 quad_perm:[1,0,3,2] row_mask:0xf bank_mask:0xf bound_ctrl:1
	v_fmac_f32_e32 v151, v147, v147
	v_add_f32_e32 v145, -1.0, v144
	v_fma_f32 v145, v192, v145, 1.0
	v_add_f32_dpp v151, v151, v151 quad_perm:[2,3,0,1] row_mask:0xf bank_mask:0xf bound_ctrl:1
	v_mul_f32_e32 v164, v135, v145
	v_mov_b32_e32 v162, v216
	v_add_f32_dpp v151, v151, v151 row_ror:4 row_mask:0xf bank_mask:0xf bound_ctrl:1
	v_mov_b32_e32 v221, v184
	s_nop 0
	v_add_f32_dpp v151, v151, v151 row_ror:8 row_mask:0xf bank_mask:0xf bound_ctrl:1
	v_mov_b32_e32 v153, v151
	s_nop 1
	v_permlane16_swap_b32_e32 v151, v153
	v_add_f32_e32 v151, v151, v153
	v_mov_b32_e32 v153, v151
	s_nop 1
	v_permlane32_swap_b32_e32 v151, v153
	v_add_f32_e32 v151, v151, v153
	v_max_f32_e32 v151, 0x2b8cbccc, v151
	v_rsq_f32_e32 v151, v151
	v_mov_b32_e32 v153, v185
	v_mul_f32_e32 v163, v147, v151
	v_mul_f32_e32 v218, v144, v163
	v_mul_f32_e32 v135, v143, v218
	s_nop 1
	v_mov_b32_dpp v135, v135 quad_perm:[1,0,3,2] row_mask:0xf bank_mask:0xf bound_ctrl:1
	v_fmac_f32_e32 v135, v143, v218
	s_nop 1
	v_add_f32_dpp v135, v135, v135 quad_perm:[2,3,0,1] row_mask:0xf bank_mask:0xf bound_ctrl:1
	s_nop 1
	v_add_f32_dpp v135, v135, v135 row_ror:4 row_mask:0xf bank_mask:0xf bound_ctrl:1
	s_nop 1
	v_add_f32_dpp v135, v135, v135 row_ror:8 row_mask:0xf bank_mask:0xf bound_ctrl:1
	v_mov_b32_e32 v144, v135
	s_nop 1
	v_permlane16_swap_b32_e32 v135, v144
	v_add_f32_e32 v144, v135, v144
	v_mul_f32_e32 v135, v143, v164
	v_mul_f32_e32 v150, v197, v135
	v_mov_b32_e32 v146, v144
	v_mov_b32_dpp v145, v135 quad_perm:[1,0,3,2] row_mask:0xf bank_mask:0xf bound_ctrl:1
	v_mov_b32_dpp v150, v150 quad_perm:[1,0,3,2] row_mask:0xf bank_mask:0xf bound_ctrl:1
	v_fmac_f32_e32 v145, v143, v164
	v_fmac_f32_e32 v150, v197, v135
	v_permlane32_swap_b32_e32 v144, v146
	v_add_f32_dpp v145, v145, v145 quad_perm:[2,3,0,1] row_mask:0xf bank_mask:0xf bound_ctrl:1
	v_add_f32_dpp v135, v150, v150 quad_perm:[2,3,0,1] row_mask:0xf bank_mask:0xf bound_ctrl:1
	s_nop 0
	v_add_f32_dpp v145, v145, v145 row_ror:4 row_mask:0xf bank_mask:0xf bound_ctrl:1
	v_add_f32_dpp v135, v135, v135 row_ror:4 row_mask:0xf bank_mask:0xf bound_ctrl:1
	s_nop 0
	v_add_f32_dpp v145, v145, v145 row_ror:8 row_mask:0xf bank_mask:0xf bound_ctrl:1
	v_add_f32_dpp v135, v135, v135 row_ror:8 row_mask:0xf bank_mask:0xf bound_ctrl:1
	v_mov_b32_e32 v147, v145
	v_mov_b32_e32 v150, v135
	s_nop 0
	v_permlane16_swap_b32_e32 v145, v147
	v_permlane16_swap_b32_e32 v135, v150
	v_add_f32_e32 v145, v145, v147
	v_add_f32_e32 v219, v135, v150
	v_mov_b32_e32 v147, v145
	v_mov_b32_e32 v220, v219
	s_nop 0
	v_permlane32_swap_b32_e32 v145, v147
	v_permlane32_swap_b32_e32 v219, v220
	s_cbranch_scc1 .LBB0_817
	s_add_i32 s2, s23, 0xffffbb80
	v_mad_u64_u32 v[150:151], s[2:3], s2, v210, v[178:179]
	global_load_dword v221, v[150:151], off
	global_load_dword v153, v[150:151], off offset:1536
	global_load_dword v162, v[150:151], off offset:3072

; __device__ __forceinline__ float bf2f(bf16_t b) { return __uint_as_float(((unsigned)b) << 16); }
; __device__ __forceinline__ void prep_produce(const Params& P, const bf16_t* __restrict__ prw, int ch, float* buf, int j, float mux) {
;     ...
;     const int tok0 = ch * CT;
;     float pv = 0.f;
;     if (tok0 < NTOK && (tok0 & (SEQ - 1))) pv = bf2f(prw[(size_t)(tok0 - 1) * RCOLS + 1152 + j]);
;     float cur[CT];
; #pragma unroll
;     for (int tk = 0; tk < CT; ++tk) cur[tk] = bf2f(prw[(size_t)(tok0 + tk) * RCOLS + 1152 + j]);
; __device__ __forceinline__ void p2_rwkv_prep(const Params& P, float* lds) {
;     ...
;         if (tid >= RW) { if (ch + NPREP < NCHK) prep_produce(P, prw, ch + NPREP, bufn, tid - RW, mux); }
.LBB0_834:
	s_andn2_saveexec_b64 s[0:1], s[0:1]
	s_cbranch_execz .LBB0_763
	s_cmpk_gt_i32 s30, 0x773
	s_cbranch_scc1 .LBB0_763
	s_add_i32 s16, s30, 0x90
	s_cmpk_gt_i32 s30, 0x76f
	s_cselect_b64 s[2:3], -1, 0
	s_and_b32 s16, s16, 0x1ff
	s_cmp_eq_u32 s16, 0
	s_cselect_b64 s[16:17], -1, 0
	s_or_b64 s[16:17], s[2:3], s[16:17]
	v_mov_b32_e32 v130, 0
	s_and_b64 vcc, exec, s[16:17]
	s_cbranch_vccnz .LBB0_838
	s_add_i32 s16, s23, -8
	v_mad_i64_i32 v[130:131], s[16:17], s16, v208, v[180:181]
	global_load_ushort v1, v[130:131], off offset:2304
	s_waitcnt vmcnt(0)
	v_lshlrev_b32_e32 v130, 16, v1

; #define LAS __attribute__((address_space(3)))
; __device__ __forceinline__ unsigned xb_ld(unsigned* p)              { return __hip_atomic_load(p, __ATOMIC_RELAXED, __HIP_MEMORY_SCOPE_AGENT); }
; __device__ __forceinline__ void sb_decode_wave_loop(const Params& P, float* lds) {
;     unsigned* qd = (unsigned*)(P.ws + WS_BAR) + QW_DEC;
;     const int lane = threadIdx.x & 63;
;     volatile LAS unsigned* scw = (volatile LAS unsigned*)((LAS unsigned char*)lds + SC_CTL_OFF_FWD);
;     unsigned nxt = 0u;
;     if (lane == 0) nxt = atomicAdd(qd, 2u);
;     for (;;) {
;         const int t = __builtin_amdgcn_readfirstlane((int)nxt);
;         if (t >= DEC_NTASK) break;
;         if (lane == 0) nxt = atomicAdd(qd, 2u);
; __device__ __forceinline__ void p3_scan_and_sb(const Params& P, float* lds) {
;     ...
;     if (blockIdx.x < 96) {
;         const int bh = blockIdx.x >> 2, quarter = blockIdx.x & 3, b = bh / RH, h = bh % RH;
;         volatile LAS unsigned* scw = (volatile LAS unsigned*)((LAS unsigned char*)lds + SC_CTL_OFF);
;         if (tid < 5) scw[tid] = 0u;
;         if (tid == 0) { XB_SPIN(xb_ld(ctl + QW_PREP_W) < (unsigned)NPREP, ctl); __builtin_amdgcn_fence(__ATOMIC_ACQUIRE, "agent"); asm volatile("s_waitcnt vmcnt(0)" ::: "memory"); }
;         __syncthreads();
;         scan_prompt_wave(P, (unsigned char*)lds, b, h, quarter);
;         if (wave >= 5 + SC_FREE_WAVES) {
;             constexpr unsigned NCHU = SEQ / SCH;
;             while (scw[1] < NCHU || scw[2] < NCHU || scw[3] < NCHU || scw[4] < NCHU) __builtin_amdgcn_s_sleep(32);
;         }
;     } else {
;         const int grp = wave >> 2, gw = wave & 3;
;         volatile LAS unsigned* gctl = (volatile LAS unsigned*)((LAS unsigned char*)lds + LDS_CTL + 32);
;         if (tid < 8) gctl[tid] = 0u;
;         __syncthreads();
;         sba::Grp4 G; G.ctr = gctl + grp; G.gen = 0u;
;         if (grp == 1) sb_decode_wave_loop(P, lds);
;         {
;             volatile LAS unsigned* qw = gctl + 4 + grp;
;             unsigned* qhead = (unsigned*)(P.ws + WS_BAR) + QW_SB;
;             const bool popper = (gw == 0 && lane == 0);
;             unsigned nxt = 0u;
;             if (popper) nxt = atomicAdd(qhead, 1u);
.LBB0_939:
	s_cmp_lt_i32 s60, 4
	s_cselect_b64 s[0:1], -1, 0
	s_cmp_gt_i32 s61, 3
	s_cselect_b64 s[2:3], -1, 0
	s_and_b64 s[34:35], s[0:1], s[2:3]
	s_andn2_b64 vcc, exec, s[34:35]
	s_cbranch_vccnz .LBB0_1576
	v_writelane_b32 v252, s34, 54
	s_cmpk_lt_u32 s56, 0x60
	v_and_b32_e32 v1, 63, v0
	v_writelane_b32 v252, s35, 55
	v_writelane_b32 v252, s80, 56
	s_cselect_b64 s[52:53], -1, 0
	s_cmpk_gt_u32 s56, 0x5f
	v_writelane_b32 v252, s81, 57
	v_writelane_b32 v252, s56, 53
	v_writelane_b32 v252, s60, 51
	s_mov_b64 s[0:1], -1
	s_waitcnt vmcnt(0)
	v_writelane_b32 v252, s61, 52
	s_barrier
	v_writelane_b32 v252, s57, 50
	s_cbranch_scc0 .LBB0_1203
	v_writelane_b32 v252, s52, 58
	v_cmp_gt_u32_e32 vcc, 8, v0
	s_nop 0
	v_writelane_b32 v252, s53, 59
	s_and_saveexec_b64 s[0:1], vcc
	v_lshl_add_u32 v2, v0, 2, 0
	v_add_u32_e32 v2, 0x26020, v2
	v_mov_b32_e32 v3, 0
	ds_write_b32 v2, v3
	s_or_b64 exec, exec, s[0:1]
	v_lshrrev_b32_e32 v94, 8, v0
	s_waitcnt lgkmcnt(0)
	s_barrier
	v_cmp_eq_u32_e32 vcc, 1, v94
	s_mov_b64 s[0:1], exec
	v_writelane_b32 v252, s0, 60
	s_nop 1
	v_writelane_b32 v252, s1, 61
	s_cmpk_gt_u32 s56, 0x8f
	s_cselect_b64 s[2:3], exec, 0
	s_or_b64 vcc, vcc, s[2:3]
	s_and_b64 s[0:1], s[0:1], vcc
	s_mov_b64 exec, s[0:1]
	s_cbranch_execz .LBB0_1092
	v_readfirstlane_b32 s2, v94
	s_cmp_eq_u32 s2, 0
	s_cselect_b32 s100, 2, 0x7fffffff
	s_add_u32 s0, s78, 0x3900
	s_addc_u32 s1, s79, 0
	v_writelane_b32 v252, s0, 62
	v_mov_b32_e32 v95, 0
	v_cmp_eq_u32_e64 s[4:5], 0, v1
	v_writelane_b32 v252, s1, 63
	s_and_saveexec_b64 s[0:1], s[4:5]
	v_readlane_b32 s22, v252, 48
	v_readlane_b32 s23, v252, 49
	s_cbranch_execz .LBB0_948
	s_mov_b64 s[6:7], exec
	v_mbcnt_lo_u32_b32 v2, s6, 0
	v_mbcnt_hi_u32_b32 v2, s7, v2
	v_cmp_eq_u32_e32 vcc, 0, v2
	s_and_saveexec_b64 s[2:3], vcc
	s_cbranch_execz .LBB0_947
	s_bcnt1_i32_b64 s6, s[6:7]
	s_lshl_b32 s6, s6, 1
	v_mov_b32_e32 v4, s6
	v_readlane_b32 s6, v252, 62
	v_mov_b32_e32 v3, 0
	v_readlane_b32 s7, v252, 63
	s_nop 4
	global_atomic_add v3, v3, v4, s[6:7] sc0

; #define LAS __attribute__((address_space(3)))
; __device__ __forceinline__ unsigned xb_ld(unsigned* p)              { return __hip_atomic_load(p, __ATOMIC_RELAXED, __HIP_MEMORY_SCOPE_AGENT); }
; #define XB_SPIN(cond, bar) do { unsigned _sp = 0; while (cond) { __builtin_amdgcn_s_sleep(1); \
;     if ((++_sp & 255u) == 0u) { if (xb_ld(&(bar)[XB_TMO])) break; if (_sp > XB_SPIN_CAP) { atomicAdd(&(bar)[XB_TMO], 1u); break; } } } } while (0)
; __device__ __forceinline__ void p3_scan_and_sb(const Params& P, float* lds) {
;     ...
;     if (blockIdx.x < 96) {
;         const int bh = blockIdx.x >> 2, quarter = blockIdx.x & 3, b = bh / RH, h = bh % RH;
;         volatile LAS unsigned* scw = (volatile LAS unsigned*)((LAS unsigned char*)lds + SC_CTL_OFF);
;         if (tid < 5) scw[tid] = 0u;
;         if (tid == 0) { XB_SPIN(xb_ld(ctl + QW_PREP_W) < (unsigned)NPREP, ctl); __builtin_amdgcn_fence(__ATOMIC_ACQUIRE, "agent"); asm volatile("s_waitcnt vmcnt(0)" ::: "memory"); }
;         __syncthreads();
.LBB0_1203:
	s_and_b64 vcc, exec, s[0:1]
	s_cbranch_vccz .LBB0_1261
	v_cmp_gt_u32_e32 vcc, 5, v0
	s_and_saveexec_b64 s[0:1], vcc
	v_lshl_add_u32 v2, v0, 2, 0
	v_add_u32_e32 v2, 0x23000, v2
	v_mov_b32_e32 v3, 0
	ds_write_b32 v2, v3
	s_or_b64 exec, exec, s[0:1]
	s_and_saveexec_b64 s[0:1], s[80:81]
	s_cbranch_execz .LBB0_1221
	v_mov_b32_e32 v2, 0x3000
	global_load_dword v2, v2, s[78:79] offset:3328 sc1
	s_movk_i32 s10, 0x8f
	s_add_u32 s2, s78, 0x3d00
	s_addc_u32 s3, s79, 0
	s_waitcnt vmcnt(0)
	v_cmp_lt_u32_e32 vcc, s10, v2
	s_cbranch_vccnz .LBB0_1220
	s_mov_b32 s11, 1
	v_mov_b32_e32 v2, 0
	s_branch .LBB0_1210

; __device__ __forceinline__ unsigned xb_ld(unsigned* p)              { return __hip_atomic_load(p, __ATOMIC_RELAXED, __HIP_MEMORY_SCOPE_AGENT); }
; #define XB_SPIN(cond, bar) do { unsigned _sp = 0; while (cond) { __builtin_amdgcn_s_sleep(1); \
;     if ((++_sp & 255u) == 0u) { if (xb_ld(&(bar)[XB_TMO])) break; if (_sp > XB_SPIN_CAP) { atomicAdd(&(bar)[XB_TMO], 1u); break; } } } } while (0)
; __device__ __forceinline__ void p3_scan_and_sb(const Params& P, float* lds) {
;     ...
;     sb_decode_wave_loop(P, lds);
;     if (lane == 0) XB_SPIN(xb_ld(ctl + QW_PREP_W) < (unsigned)NPREP, ctl);
;     __builtin_amdgcn_fence(__ATOMIC_ACQUIRE, "agent");
.LBB0_1555:
	s_and_saveexec_b64 s[0:1], s[4:5]
	v_readlane_b32 s58, v252, 48
	v_readlane_b32 s59, v252, 49
	s_load_dwordx8 s[68:75], s[58:59], 0xc0
	v_readlane_b32 s80, v252, 56
	v_readlane_b32 s60, v252, 51
	v_readlane_b32 s34, v252, 54
	v_readlane_b32 s81, v252, 57
	v_readlane_b32 s56, v252, 53
	v_readlane_b32 s61, v252, 52
	v_readlane_b32 s57, v252, 50
	v_readlane_b32 s35, v252, 55
	s_cbranch_execz .LBB0_1568
	v_mov_b32_e32 v1, 0x3000
	global_load_dword v1, v1, s[78:79] offset:3328 sc1
	s_movk_i32 s10, 0x8f
	s_add_u32 s2, s78, 0x3d00
	s_addc_u32 s3, s79, 0
	s_waitcnt vmcnt(0)
	v_cmp_lt_u32_e32 vcc, s10, v1
	s_cbranch_vccnz .LBB0_1568
	s_mov_b32 s11, 1
	v_mov_b32_e32 v1, 0
	s_branch .LBB0_1559
